# new 2-deep pipelined w_in f32->bf16 transpose-convert loop (saddr addressing) + scalarised packed-f32 VALU in diff-attention loop
# baseline (speedup 1.0000x reference)
.LBB0_18:
	s_waitcnt lgkmcnt(0)
	s_load_dwordx2 s[30:31], s[88:89], 0x20
	s_load_dwordx2 s[32:33], s[88:89], 0x98
	v_mbcnt_lo_u32_b32 v2, -1, 0
	v_mbcnt_hi_u32_b32 v2, -1, v2
	s_lshl_b32 s34, s2, 3
	s_add_i32 s34, s34, s79
	s_lshl_b32 s35, s80, 3
	s_lshl_b32 s36, s79, 14
	s_mov_b32 s50, 0x6234c20
	s_mov_b32 s51, 0x491053d
	v_lshrrev_b32_e32 v3, 5, v2
	v_and_b32_e32 v4, 31, v2
	v_mov_b32_e32 v8, 0x14000
	v_mul_lo_u32 v5, v3, v8
	v_lshl_add_u32 v5, v4, 2, v5
	v_mul_u32_u24_e32 v6, 33, v3
	v_add_u32_e32 v6, v6, v4
	v_lshl_add_u32 v6, v6, 2, s36
	v_and_b32_e32 v10, 7, v2
	v_mul_u32_u24_e32 v7, 0x108, v10
	v_lshrrev_b32_e32 v8, 3, v2
	v_add_u32_e32 v7, v7, v8
	v_lshl_add_u32 v7, v7, 2, s36
	v_lshlrev_b32_e32 v9, 12, v8
	v_lshl_add_u32 v9, v10, 4, v9
	s_waitcnt lgkmcnt(0)
	s_cmp_ge_u32 s34, 0xa000
	s_cbranch_scc1 .Lcv_done
	s_cmp_ge_u32 s34, 0x5000
	s_cselect_b32 s38, 1, 0
	s_mul_i32 s39, s38, 0x5000
	s_sub_u32 s39, s34, s39
	s_lshr_b32 s40, s39, 3
	s_mul_i32 s41, s40, 0xcccd
	s_lshr_b32 s41, s41, 24
	s_mul_i32 s42, s41, 0x140
	s_sub_u32 s40, s40, s42
	s_lshl_b32 s40, s40, 1
	s_bfe_u32 s42, s39, 0x10002
	s_add_u32 s40, s40, s42
	s_lshl_b32 s41, s41, 2
	s_and_b32 s42, s39, 3
	s_add_u32 s41, s41, s42
	s_lshl_b32 s41, s41, 6
	s_lshl_b32 s40, s40, 5
	s_mul_i32 s42, s38, 0xa000000
	s_mul_i32 s43, s41, 0x14000
	s_add_u32 s42, s42, s43
	s_lshl_b32 s43, s40, 2
	s_add_u32 s42, s42, s43
	s_add_u32 s48, s30, s42
	s_addc_u32 s49, s31, 0
	s_lshr_b32 s42, s40, 10
	s_min_u32 s43, s42, 11
	s_mul_i32 s43, s43, 5
	s_lshr_b64 s[52:53], s[50:51], s43
	s_and_b32 s52, s52, 31
	s_sub_u32 s53, s42, 2
	s_cmp_ge_u32 s42, 12
	s_cselect_b32 s42, s53, s52
	s_lshl_b32 s42, s42, 10
	s_and_b32 s43, s40, 0x3ff
	s_add_u32 s42, s42, s43
	s_lshl_b32 s42, s42, 12
	s_lshl_b32 s43, s41, 1
	s_add_u32 s42, s42, s43
	s_mul_i32 s43, s38, 0x7100000
	s_add_u32 s42, s42, s43
	s_add_u32 s42, s42, 0x200000
	s_add_u32 s44, s32, s42
	s_addc_u32 s45, s33, 0
	global_load_dword v16, v5, s[48:49]
	v_add_u32_e32 v11, 0x28000, v5
	global_load_dword v17, v11, s[48:49]
	v_add_u32_e32 v11, 0x50000, v5
	global_load_dword v18, v11, s[48:49]
	v_add_u32_e32 v11, 0x78000, v5
	global_load_dword v19, v11, s[48:49]
	v_add_u32_e32 v11, 0xa0000, v5
	global_load_dword v20, v11, s[48:49]
	v_add_u32_e32 v11, 0xc8000, v5
	global_load_dword v21, v11, s[48:49]
	v_add_u32_e32 v11, 0xf0000, v5
	global_load_dword v22, v11, s[48:49]
	v_add_u32_e32 v11, 0x118000, v5
	global_load_dword v23, v11, s[48:49]
	v_add_u32_e32 v11, 0x140000, v5
	global_load_dword v24, v11, s[48:49]
	v_add_u32_e32 v11, 0x168000, v5
	global_load_dword v25, v11, s[48:49]
	v_add_u32_e32 v11, 0x190000, v5
	global_load_dword v26, v11, s[48:49]
	v_add_u32_e32 v11, 0x1b8000, v5
	global_load_dword v27, v11, s[48:49]
	v_add_u32_e32 v11, 0x1e0000, v5
	global_load_dword v28, v11, s[48:49]
	v_add_u32_e32 v11, 0x208000, v5
	global_load_dword v29, v11, s[48:49]
	v_add_u32_e32 v11, 0x230000, v5
	global_load_dword v30, v11, s[48:49]
	v_add_u32_e32 v11, 0x258000, v5
	global_load_dword v31, v11, s[48:49]
	v_add_u32_e32 v11, 0x280000, v5
	global_load_dword v32, v11, s[48:49]
	v_add_u32_e32 v11, 0x2a8000, v5
	global_load_dword v33, v11, s[48:49]
	v_add_u32_e32 v11, 0x2d0000, v5
	global_load_dword v34, v11, s[48:49]
	v_add_u32_e32 v11, 0x2f8000, v5
	global_load_dword v35, v11, s[48:49]
	v_add_u32_e32 v11, 0x320000, v5
	global_load_dword v36, v11, s[48:49]
	v_add_u32_e32 v11, 0x348000, v5
	global_load_dword v37, v11, s[48:49]
	v_add_u32_e32 v11, 0x370000, v5
	global_load_dword v38, v11, s[48:49]
	v_add_u32_e32 v11, 0x398000, v5
	global_load_dword v39, v11, s[48:49]
	v_add_u32_e32 v11, 0x3c0000, v5
	global_load_dword v40, v11, s[48:49]
	v_add_u32_e32 v11, 0x3e8000, v5
	global_load_dword v41, v11, s[48:49]
	v_add_u32_e32 v11, 0x410000, v5
	global_load_dword v42, v11, s[48:49]
	v_add_u32_e32 v11, 0x438000, v5
	global_load_dword v43, v11, s[48:49]
	v_add_u32_e32 v11, 0x460000, v5
	global_load_dword v44, v11, s[48:49]
	v_add_u32_e32 v11, 0x488000, v5
	global_load_dword v45, v11, s[48:49]
	v_add_u32_e32 v11, 0x4b0000, v5
	global_load_dword v46, v11, s[48:49]
	v_add_u32_e32 v11, 0x4d8000, v5
	global_load_dword v47, v11, s[48:49]
.Lcv_loop:
	s_add_u32 s37, s34, s35
	s_cmp_ge_u32 s37, 0xa000
	s_cbranch_scc1 .Lcv_lastA
	s_cmp_ge_u32 s37, 0x5000
	s_cselect_b32 s38, 1, 0
	s_mul_i32 s39, s38, 0x5000
	s_sub_u32 s39, s37, s39
	s_lshr_b32 s40, s39, 3
	s_mul_i32 s41, s40, 0xcccd
	s_lshr_b32 s41, s41, 24
	s_mul_i32 s42, s41, 0x140
	s_sub_u32 s40, s40, s42
	s_lshl_b32 s40, s40, 1
	s_bfe_u32 s42, s39, 0x10002
	s_add_u32 s40, s40, s42
	s_lshl_b32 s41, s41, 2
	s_and_b32 s42, s39, 3
	s_add_u32 s41, s41, s42
	s_lshl_b32 s41, s41, 6
	s_lshl_b32 s40, s40, 5
	s_mul_i32 s42, s38, 0xa000000
	s_mul_i32 s43, s41, 0x14000
	s_add_u32 s42, s42, s43
	s_lshl_b32 s43, s40, 2
	s_add_u32 s42, s42, s43
	s_add_u32 s48, s30, s42
	s_addc_u32 s49, s31, 0
	s_lshr_b32 s42, s40, 10
	s_min_u32 s43, s42, 11
	s_mul_i32 s43, s43, 5
	s_lshr_b64 s[52:53], s[50:51], s43
	s_and_b32 s52, s52, 31
	s_sub_u32 s53, s42, 2
	s_cmp_ge_u32 s42, 12
	s_cselect_b32 s42, s53, s52
	s_lshl_b32 s42, s42, 10
	s_and_b32 s43, s40, 0x3ff
	s_add_u32 s42, s42, s43
	s_lshl_b32 s42, s42, 12
	s_lshl_b32 s43, s41, 1
	s_add_u32 s42, s42, s43
	s_mul_i32 s43, s38, 0x7100000
	s_add_u32 s42, s42, s43
	s_add_u32 s42, s42, 0x200000
	s_add_u32 s46, s32, s42
	s_addc_u32 s47, s33, 0
	global_load_dword v48, v5, s[48:49]
	v_add_u32_e32 v11, 0x28000, v5
	global_load_dword v49, v11, s[48:49]
	v_add_u32_e32 v11, 0x50000, v5
	global_load_dword v50, v11, s[48:49]
	v_add_u32_e32 v11, 0x78000, v5
	global_load_dword v51, v11, s[48:49]
	v_add_u32_e32 v11, 0xa0000, v5
	global_load_dword v52, v11, s[48:49]
	v_add_u32_e32 v11, 0xc8000, v5
	global_load_dword v53, v11, s[48:49]
	v_add_u32_e32 v11, 0xf0000, v5
	global_load_dword v54, v11, s[48:49]
	v_add_u32_e32 v11, 0x118000, v5
	global_load_dword v55, v11, s[48:49]
	v_add_u32_e32 v11, 0x140000, v5
	global_load_dword v56, v11, s[48:49]
	v_add_u32_e32 v11, 0x168000, v5
	global_load_dword v57, v11, s[48:49]
	v_add_u32_e32 v11, 0x190000, v5
	global_load_dword v58, v11, s[48:49]
	v_add_u32_e32 v11, 0x1b8000, v5
	global_load_dword v59, v11, s[48:49]
	v_add_u32_e32 v11, 0x1e0000, v5
	global_load_dword v60, v11, s[48:49]
	v_add_u32_e32 v11, 0x208000, v5
	global_load_dword v61, v11, s[48:49]
	v_add_u32_e32 v11, 0x230000, v5
	global_load_dword v62, v11, s[48:49]
	v_add_u32_e32 v11, 0x258000, v5
	global_load_dword v63, v11, s[48:49]
	v_add_u32_e32 v11, 0x280000, v5
	global_load_dword v64, v11, s[48:49]
	v_add_u32_e32 v11, 0x2a8000, v5
	global_load_dword v65, v11, s[48:49]
	v_add_u32_e32 v11, 0x2d0000, v5
	global_load_dword v66, v11, s[48:49]
	v_add_u32_e32 v11, 0x2f8000, v5
	global_load_dword v67, v11, s[48:49]
	v_add_u32_e32 v11, 0x320000, v5
	global_load_dword v68, v11, s[48:49]
	v_add_u32_e32 v11, 0x348000, v5
	global_load_dword v69, v11, s[48:49]
	v_add_u32_e32 v11, 0x370000, v5
	global_load_dword v70, v11, s[48:49]
	v_add_u32_e32 v11, 0x398000, v5
	global_load_dword v71, v11, s[48:49]
	v_add_u32_e32 v11, 0x3c0000, v5
	global_load_dword v72, v11, s[48:49]
	v_add_u32_e32 v11, 0x3e8000, v5
	global_load_dword v73, v11, s[48:49]
	v_add_u32_e32 v11, 0x410000, v5
	global_load_dword v74, v11, s[48:49]
	v_add_u32_e32 v11, 0x438000, v5
	global_load_dword v75, v11, s[48:49]
	v_add_u32_e32 v11, 0x460000, v5
	global_load_dword v76, v11, s[48:49]
	v_add_u32_e32 v11, 0x488000, v5
	global_load_dword v77, v11, s[48:49]
	v_add_u32_e32 v11, 0x4b0000, v5
	global_load_dword v78, v11, s[48:49]
	v_add_u32_e32 v11, 0x4d8000, v5
	global_load_dword v79, v11, s[48:49]
	s_waitcnt vmcnt(32)
	ds_write_b32 v6, v16
	ds_write_b32 v6, v17 offset:264
	ds_write_b32 v6, v18 offset:528
	ds_write_b32 v6, v19 offset:792
	ds_write_b32 v6, v20 offset:1056
	ds_write_b32 v6, v21 offset:1320
	ds_write_b32 v6, v22 offset:1584
	ds_write_b32 v6, v23 offset:1848
	ds_write_b32 v6, v24 offset:2112
	ds_write_b32 v6, v25 offset:2376
	ds_write_b32 v6, v26 offset:2640
	ds_write_b32 v6, v27 offset:2904
	ds_write_b32 v6, v28 offset:3168
	ds_write_b32 v6, v29 offset:3432
	ds_write_b32 v6, v30 offset:3696
	ds_write_b32 v6, v31 offset:3960
	ds_write_b32 v6, v32 offset:4224
	ds_write_b32 v6, v33 offset:4488
	ds_write_b32 v6, v34 offset:4752
	ds_write_b32 v6, v35 offset:5016
	ds_write_b32 v6, v36 offset:5280
	ds_write_b32 v6, v37 offset:5544
	ds_write_b32 v6, v38 offset:5808
	ds_write_b32 v6, v39 offset:6072
	ds_write_b32 v6, v40 offset:6336
	ds_write_b32 v6, v41 offset:6600
	ds_write_b32 v6, v42 offset:6864
	ds_write_b32 v6, v43 offset:7128
	ds_write_b32 v6, v44 offset:7392
	ds_write_b32 v6, v45 offset:7656
	ds_write_b32 v6, v46 offset:7920
	ds_write_b32 v6, v47 offset:8184
	s_waitcnt lgkmcnt(0)
	ds_read2_b32 v[16:17], v7 offset0:0 offset1:33
	ds_read2_b32 v[18:19], v7 offset0:66 offset1:99
	ds_read2_b32 v[20:21], v7 offset0:132 offset1:165
	ds_read2_b32 v[22:23], v7 offset0:198 offset1:231
	ds_read2_b32 v[24:25], v7 offset0:8 offset1:41
	ds_read2_b32 v[26:27], v7 offset0:74 offset1:107
	ds_read2_b32 v[28:29], v7 offset0:140 offset1:173
	ds_read2_b32 v[30:31], v7 offset0:206 offset1:239
	ds_read2_b32 v[32:33], v7 offset0:16 offset1:49
	ds_read2_b32 v[34:35], v7 offset0:82 offset1:115
	ds_read2_b32 v[36:37], v7 offset0:148 offset1:181
	ds_read2_b32 v[38:39], v7 offset0:214 offset1:247
	ds_read2_b32 v[40:41], v7 offset0:24 offset1:57
	ds_read2_b32 v[42:43], v7 offset0:90 offset1:123
	ds_read2_b32 v[44:45], v7 offset0:156 offset1:189
	ds_read2_b32 v[46:47], v7 offset0:222 offset1:255
	s_waitcnt lgkmcnt(12)
	v_cvt_pk_bf16_f32 v12, v16, v17
	v_cvt_pk_bf16_f32 v13, v18, v19
	v_cvt_pk_bf16_f32 v14, v20, v21
	v_cvt_pk_bf16_f32 v15, v22, v23
	global_store_dwordx4 v9, v[12:15], s[44:45]
	s_waitcnt lgkmcnt(8)
	v_cvt_pk_bf16_f32 v80, v24, v25
	v_cvt_pk_bf16_f32 v81, v26, v27
	v_cvt_pk_bf16_f32 v82, v28, v29
	v_cvt_pk_bf16_f32 v83, v30, v31
	v_add_u32_e32 v11, 0x8000, v9
	global_store_dwordx4 v11, v[80:83], s[44:45]
	s_waitcnt lgkmcnt(4)
	v_cvt_pk_bf16_f32 v12, v32, v33
	v_cvt_pk_bf16_f32 v13, v34, v35
	v_cvt_pk_bf16_f32 v14, v36, v37
	v_cvt_pk_bf16_f32 v15, v38, v39
	v_add_u32_e32 v11, 0x10000, v9
	global_store_dwordx4 v11, v[12:15], s[44:45]
	s_waitcnt lgkmcnt(0)
	v_cvt_pk_bf16_f32 v80, v40, v41
	v_cvt_pk_bf16_f32 v81, v42, v43
	v_cvt_pk_bf16_f32 v82, v44, v45
	v_cvt_pk_bf16_f32 v83, v46, v47
	v_add_u32_e32 v11, 0x18000, v9
	global_store_dwordx4 v11, v[80:83], s[44:45]
	s_add_u32 s34, s37, s35
	s_cmp_ge_u32 s34, 0xa000
	s_cbranch_scc1 .Lcv_lastB
	s_cmp_ge_u32 s34, 0x5000
	s_cselect_b32 s38, 1, 0
	s_mul_i32 s39, s38, 0x5000
	s_sub_u32 s39, s34, s39
	s_lshr_b32 s40, s39, 3
	s_mul_i32 s41, s40, 0xcccd
	s_lshr_b32 s41, s41, 24
	s_mul_i32 s42, s41, 0x140
	s_sub_u32 s40, s40, s42
	s_lshl_b32 s40, s40, 1
	s_bfe_u32 s42, s39, 0x10002
	s_add_u32 s40, s40, s42
	s_lshl_b32 s41, s41, 2
	s_and_b32 s42, s39, 3
	s_add_u32 s41, s41, s42
	s_lshl_b32 s41, s41, 6
	s_lshl_b32 s40, s40, 5
	s_mul_i32 s42, s38, 0xa000000
	s_mul_i32 s43, s41, 0x14000
	s_add_u32 s42, s42, s43
	s_lshl_b32 s43, s40, 2
	s_add_u32 s42, s42, s43
	s_add_u32 s48, s30, s42
	s_addc_u32 s49, s31, 0
	s_lshr_b32 s42, s40, 10
	s_min_u32 s43, s42, 11
	s_mul_i32 s43, s43, 5
	s_lshr_b64 s[52:53], s[50:51], s43
	s_and_b32 s52, s52, 31
	s_sub_u32 s53, s42, 2
	s_cmp_ge_u32 s42, 12
	s_cselect_b32 s42, s53, s52
	s_lshl_b32 s42, s42, 10
	s_and_b32 s43, s40, 0x3ff
	s_add_u32 s42, s42, s43
	s_lshl_b32 s42, s42, 12
	s_lshl_b32 s43, s41, 1
	s_add_u32 s42, s42, s43
	s_mul_i32 s43, s38, 0x7100000
	s_add_u32 s42, s42, s43
	s_add_u32 s42, s42, 0x200000
	s_add_u32 s44, s32, s42
	s_addc_u32 s45, s33, 0
	global_load_dword v16, v5, s[48:49]
	v_add_u32_e32 v11, 0x28000, v5
	global_load_dword v17, v11, s[48:49]
	v_add_u32_e32 v11, 0x50000, v5
	global_load_dword v18, v11, s[48:49]
	v_add_u32_e32 v11, 0x78000, v5
	global_load_dword v19, v11, s[48:49]
	v_add_u32_e32 v11, 0xa0000, v5
	global_load_dword v20, v11, s[48:49]
	v_add_u32_e32 v11, 0xc8000, v5
	global_load_dword v21, v11, s[48:49]
	v_add_u32_e32 v11, 0xf0000, v5
	global_load_dword v22, v11, s[48:49]
	v_add_u32_e32 v11, 0x118000, v5
	global_load_dword v23, v11, s[48:49]
	v_add_u32_e32 v11, 0x140000, v5
	global_load_dword v24, v11, s[48:49]
	v_add_u32_e32 v11, 0x168000, v5
	global_load_dword v25, v11, s[48:49]
	v_add_u32_e32 v11, 0x190000, v5
	global_load_dword v26, v11, s[48:49]
	v_add_u32_e32 v11, 0x1b8000, v5
	global_load_dword v27, v11, s[48:49]
	v_add_u32_e32 v11, 0x1e0000, v5
	global_load_dword v28, v11, s[48:49]
	v_add_u32_e32 v11, 0x208000, v5
	global_load_dword v29, v11, s[48:49]
	v_add_u32_e32 v11, 0x230000, v5
	global_load_dword v30, v11, s[48:49]
	v_add_u32_e32 v11, 0x258000, v5
	global_load_dword v31, v11, s[48:49]
	v_add_u32_e32 v11, 0x280000, v5
	global_load_dword v32, v11, s[48:49]
	v_add_u32_e32 v11, 0x2a8000, v5
	global_load_dword v33, v11, s[48:49]
	v_add_u32_e32 v11, 0x2d0000, v5
	global_load_dword v34, v11, s[48:49]
	v_add_u32_e32 v11, 0x2f8000, v5
	global_load_dword v35, v11, s[48:49]
	v_add_u32_e32 v11, 0x320000, v5
	global_load_dword v36, v11, s[48:49]
	v_add_u32_e32 v11, 0x348000, v5
	global_load_dword v37, v11, s[48:49]
	v_add_u32_e32 v11, 0x370000, v5
	global_load_dword v38, v11, s[48:49]
	v_add_u32_e32 v11, 0x398000, v5
	global_load_dword v39, v11, s[48:49]
	v_add_u32_e32 v11, 0x3c0000, v5
	global_load_dword v40, v11, s[48:49]
	v_add_u32_e32 v11, 0x3e8000, v5
	global_load_dword v41, v11, s[48:49]
	v_add_u32_e32 v11, 0x410000, v5
	global_load_dword v42, v11, s[48:49]
	v_add_u32_e32 v11, 0x438000, v5
	global_load_dword v43, v11, s[48:49]
	v_add_u32_e32 v11, 0x460000, v5
	global_load_dword v44, v11, s[48:49]
	v_add_u32_e32 v11, 0x488000, v5
	global_load_dword v45, v11, s[48:49]
	v_add_u32_e32 v11, 0x4b0000, v5
	global_load_dword v46, v11, s[48:49]
	v_add_u32_e32 v11, 0x4d8000, v5
	global_load_dword v47, v11, s[48:49]
	s_waitcnt vmcnt(32)
	ds_write_b32 v6, v48
	ds_write_b32 v6, v49 offset:264
	ds_write_b32 v6, v50 offset:528
	ds_write_b32 v6, v51 offset:792
	ds_write_b32 v6, v52 offset:1056
	ds_write_b32 v6, v53 offset:1320
	ds_write_b32 v6, v54 offset:1584
	ds_write_b32 v6, v55 offset:1848
	ds_write_b32 v6, v56 offset:2112
	ds_write_b32 v6, v57 offset:2376
	ds_write_b32 v6, v58 offset:2640
	ds_write_b32 v6, v59 offset:2904
	ds_write_b32 v6, v60 offset:3168
	ds_write_b32 v6, v61 offset:3432
	ds_write_b32 v6, v62 offset:3696
	ds_write_b32 v6, v63 offset:3960
	ds_write_b32 v6, v64 offset:4224
	ds_write_b32 v6, v65 offset:4488
	ds_write_b32 v6, v66 offset:4752
	ds_write_b32 v6, v67 offset:5016
	ds_write_b32 v6, v68 offset:5280
	ds_write_b32 v6, v69 offset:5544
	ds_write_b32 v6, v70 offset:5808
	ds_write_b32 v6, v71 offset:6072
	ds_write_b32 v6, v72 offset:6336
	ds_write_b32 v6, v73 offset:6600
	ds_write_b32 v6, v74 offset:6864
	ds_write_b32 v6, v75 offset:7128
	ds_write_b32 v6, v76 offset:7392
	ds_write_b32 v6, v77 offset:7656
	ds_write_b32 v6, v78 offset:7920
	ds_write_b32 v6, v79 offset:8184
	s_waitcnt lgkmcnt(0)
	ds_read2_b32 v[48:49], v7 offset0:0 offset1:33
	ds_read2_b32 v[50:51], v7 offset0:66 offset1:99
	ds_read2_b32 v[52:53], v7 offset0:132 offset1:165
	ds_read2_b32 v[54:55], v7 offset0:198 offset1:231
	ds_read2_b32 v[56:57], v7 offset0:8 offset1:41
	ds_read2_b32 v[58:59], v7 offset0:74 offset1:107
	ds_read2_b32 v[60:61], v7 offset0:140 offset1:173
	ds_read2_b32 v[62:63], v7 offset0:206 offset1:239
	ds_read2_b32 v[64:65], v7 offset0:16 offset1:49
	ds_read2_b32 v[66:67], v7 offset0:82 offset1:115
	ds_read2_b32 v[68:69], v7 offset0:148 offset1:181
	ds_read2_b32 v[70:71], v7 offset0:214 offset1:247
	ds_read2_b32 v[72:73], v7 offset0:24 offset1:57
	ds_read2_b32 v[74:75], v7 offset0:90 offset1:123
	ds_read2_b32 v[76:77], v7 offset0:156 offset1:189
	ds_read2_b32 v[78:79], v7 offset0:222 offset1:255
	s_waitcnt lgkmcnt(12)
	v_cvt_pk_bf16_f32 v12, v48, v49
	v_cvt_pk_bf16_f32 v13, v50, v51
	v_cvt_pk_bf16_f32 v14, v52, v53
	v_cvt_pk_bf16_f32 v15, v54, v55
	global_store_dwordx4 v9, v[12:15], s[46:47]
	s_waitcnt lgkmcnt(8)
	v_cvt_pk_bf16_f32 v80, v56, v57
	v_cvt_pk_bf16_f32 v81, v58, v59
	v_cvt_pk_bf16_f32 v82, v60, v61
	v_cvt_pk_bf16_f32 v83, v62, v63
	v_add_u32_e32 v11, 0x8000, v9
	global_store_dwordx4 v11, v[80:83], s[46:47]
	s_waitcnt lgkmcnt(4)
	v_cvt_pk_bf16_f32 v12, v64, v65
	v_cvt_pk_bf16_f32 v13, v66, v67
	v_cvt_pk_bf16_f32 v14, v68, v69
	v_cvt_pk_bf16_f32 v15, v70, v71
	v_add_u32_e32 v11, 0x10000, v9
	global_store_dwordx4 v11, v[12:15], s[46:47]
	s_waitcnt lgkmcnt(0)
	v_cvt_pk_bf16_f32 v80, v72, v73
	v_cvt_pk_bf16_f32 v81, v74, v75
	v_cvt_pk_bf16_f32 v82, v76, v77
	v_cvt_pk_bf16_f32 v83, v78, v79
	v_add_u32_e32 v11, 0x18000, v9
	global_store_dwordx4 v11, v[80:83], s[46:47]
	s_branch .Lcv_loop
.Lcv_lastA:
	s_waitcnt vmcnt(0)
	ds_write_b32 v6, v16
	ds_write_b32 v6, v17 offset:264
	ds_write_b32 v6, v18 offset:528
	ds_write_b32 v6, v19 offset:792
	ds_write_b32 v6, v20 offset:1056
	ds_write_b32 v6, v21 offset:1320
	ds_write_b32 v6, v22 offset:1584
	ds_write_b32 v6, v23 offset:1848
	ds_write_b32 v6, v24 offset:2112
	ds_write_b32 v6, v25 offset:2376
	ds_write_b32 v6, v26 offset:2640
	ds_write_b32 v6, v27 offset:2904
	ds_write_b32 v6, v28 offset:3168
	ds_write_b32 v6, v29 offset:3432
	ds_write_b32 v6, v30 offset:3696
	ds_write_b32 v6, v31 offset:3960
	ds_write_b32 v6, v32 offset:4224
	ds_write_b32 v6, v33 offset:4488
	ds_write_b32 v6, v34 offset:4752
	ds_write_b32 v6, v35 offset:5016
	ds_write_b32 v6, v36 offset:5280
	ds_write_b32 v6, v37 offset:5544
	ds_write_b32 v6, v38 offset:5808
	ds_write_b32 v6, v39 offset:6072
	ds_write_b32 v6, v40 offset:6336
	ds_write_b32 v6, v41 offset:6600
	ds_write_b32 v6, v42 offset:6864
	ds_write_b32 v6, v43 offset:7128
	ds_write_b32 v6, v44 offset:7392
	ds_write_b32 v6, v45 offset:7656
	ds_write_b32 v6, v46 offset:7920
	ds_write_b32 v6, v47 offset:8184
	s_waitcnt lgkmcnt(0)
	ds_read2_b32 v[16:17], v7 offset0:0 offset1:33
	ds_read2_b32 v[18:19], v7 offset0:66 offset1:99
	ds_read2_b32 v[20:21], v7 offset0:132 offset1:165
	ds_read2_b32 v[22:23], v7 offset0:198 offset1:231
	ds_read2_b32 v[24:25], v7 offset0:8 offset1:41
	ds_read2_b32 v[26:27], v7 offset0:74 offset1:107
	ds_read2_b32 v[28:29], v7 offset0:140 offset1:173
	ds_read2_b32 v[30:31], v7 offset0:206 offset1:239
	ds_read2_b32 v[32:33], v7 offset0:16 offset1:49
	ds_read2_b32 v[34:35], v7 offset0:82 offset1:115
	ds_read2_b32 v[36:37], v7 offset0:148 offset1:181
	ds_read2_b32 v[38:39], v7 offset0:214 offset1:247
	ds_read2_b32 v[40:41], v7 offset0:24 offset1:57
	ds_read2_b32 v[42:43], v7 offset0:90 offset1:123
	ds_read2_b32 v[44:45], v7 offset0:156 offset1:189
	ds_read2_b32 v[46:47], v7 offset0:222 offset1:255
	s_waitcnt lgkmcnt(12)
	v_cvt_pk_bf16_f32 v12, v16, v17
	v_cvt_pk_bf16_f32 v13, v18, v19
	v_cvt_pk_bf16_f32 v14, v20, v21
	v_cvt_pk_bf16_f32 v15, v22, v23
	global_store_dwordx4 v9, v[12:15], s[44:45]
	s_waitcnt lgkmcnt(8)
	v_cvt_pk_bf16_f32 v80, v24, v25
	v_cvt_pk_bf16_f32 v81, v26, v27
	v_cvt_pk_bf16_f32 v82, v28, v29
	v_cvt_pk_bf16_f32 v83, v30, v31
	v_add_u32_e32 v11, 0x8000, v9
	global_store_dwordx4 v11, v[80:83], s[44:45]
	s_waitcnt lgkmcnt(4)
	v_cvt_pk_bf16_f32 v12, v32, v33
	v_cvt_pk_bf16_f32 v13, v34, v35
	v_cvt_pk_bf16_f32 v14, v36, v37
	v_cvt_pk_bf16_f32 v15, v38, v39
	v_add_u32_e32 v11, 0x10000, v9
	global_store_dwordx4 v11, v[12:15], s[44:45]
	s_waitcnt lgkmcnt(0)
	v_cvt_pk_bf16_f32 v80, v40, v41
	v_cvt_pk_bf16_f32 v81, v42, v43
	v_cvt_pk_bf16_f32 v82, v44, v45
	v_cvt_pk_bf16_f32 v83, v46, v47
	v_add_u32_e32 v11, 0x18000, v9
	global_store_dwordx4 v11, v[80:83], s[44:45]
	s_branch .Lcv_done
.Lcv_lastB:
	s_waitcnt vmcnt(0)
	ds_write_b32 v6, v48
	ds_write_b32 v6, v49 offset:264
	ds_write_b32 v6, v50 offset:528
	ds_write_b32 v6, v51 offset:792
	ds_write_b32 v6, v52 offset:1056
	ds_write_b32 v6, v53 offset:1320
	ds_write_b32 v6, v54 offset:1584
	ds_write_b32 v6, v55 offset:1848
	ds_write_b32 v6, v56 offset:2112
	ds_write_b32 v6, v57 offset:2376
	ds_write_b32 v6, v58 offset:2640
	ds_write_b32 v6, v59 offset:2904
	ds_write_b32 v6, v60 offset:3168
	ds_write_b32 v6, v61 offset:3432
	ds_write_b32 v6, v62 offset:3696
	ds_write_b32 v6, v63 offset:3960
	ds_write_b32 v6, v64 offset:4224
	ds_write_b32 v6, v65 offset:4488
	ds_write_b32 v6, v66 offset:4752
	ds_write_b32 v6, v67 offset:5016
	ds_write_b32 v6, v68 offset:5280
	ds_write_b32 v6, v69 offset:5544
	ds_write_b32 v6, v70 offset:5808
	ds_write_b32 v6, v71 offset:6072
	ds_write_b32 v6, v72 offset:6336
	ds_write_b32 v6, v73 offset:6600
	ds_write_b32 v6, v74 offset:6864
	ds_write_b32 v6, v75 offset:7128
	ds_write_b32 v6, v76 offset:7392
	ds_write_b32 v6, v77 offset:7656
	ds_write_b32 v6, v78 offset:7920
	ds_write_b32 v6, v79 offset:8184
	s_waitcnt lgkmcnt(0)
	ds_read2_b32 v[48:49], v7 offset0:0 offset1:33
	ds_read2_b32 v[50:51], v7 offset0:66 offset1:99
	ds_read2_b32 v[52:53], v7 offset0:132 offset1:165
	ds_read2_b32 v[54:55], v7 offset0:198 offset1:231
	ds_read2_b32 v[56:57], v7 offset0:8 offset1:41
	ds_read2_b32 v[58:59], v7 offset0:74 offset1:107
	ds_read2_b32 v[60:61], v7 offset0:140 offset1:173
	ds_read2_b32 v[62:63], v7 offset0:206 offset1:239
	ds_read2_b32 v[64:65], v7 offset0:16 offset1:49
	ds_read2_b32 v[66:67], v7 offset0:82 offset1:115
	ds_read2_b32 v[68:69], v7 offset0:148 offset1:181
	ds_read2_b32 v[70:71], v7 offset0:214 offset1:247
	ds_read2_b32 v[72:73], v7 offset0:24 offset1:57
	ds_read2_b32 v[74:75], v7 offset0:90 offset1:123
	ds_read2_b32 v[76:77], v7 offset0:156 offset1:189
	ds_read2_b32 v[78:79], v7 offset0:222 offset1:255
	s_waitcnt lgkmcnt(12)
	v_cvt_pk_bf16_f32 v12, v48, v49
	v_cvt_pk_bf16_f32 v13, v50, v51
	v_cvt_pk_bf16_f32 v14, v52, v53
	v_cvt_pk_bf16_f32 v15, v54, v55
	global_store_dwordx4 v9, v[12:15], s[46:47]
	s_waitcnt lgkmcnt(8)
	v_cvt_pk_bf16_f32 v80, v56, v57
	v_cvt_pk_bf16_f32 v81, v58, v59
	v_cvt_pk_bf16_f32 v82, v60, v61
	v_cvt_pk_bf16_f32 v83, v62, v63
	v_add_u32_e32 v11, 0x8000, v9
	global_store_dwordx4 v11, v[80:83], s[46:47]
	s_waitcnt lgkmcnt(4)
	v_cvt_pk_bf16_f32 v12, v64, v65
	v_cvt_pk_bf16_f32 v13, v66, v67
	v_cvt_pk_bf16_f32 v14, v68, v69
	v_cvt_pk_bf16_f32 v15, v70, v71
	v_add_u32_e32 v11, 0x10000, v9
	global_store_dwordx4 v11, v[12:15], s[46:47]
	s_waitcnt lgkmcnt(0)
	v_cvt_pk_bf16_f32 v80, v72, v73
	v_cvt_pk_bf16_f32 v81, v74, v75
	v_cvt_pk_bf16_f32 v82, v76, v77
	v_cvt_pk_bf16_f32 v83, v78, v79
	v_add_u32_e32 v11, 0x18000, v9
	global_store_dwordx4 v11, v[80:83], s[46:47]
.Lcv_done:
	s_waitcnt vmcnt(0) lgkmcnt(0)
	s_lshl_b32 s0, s2, 3
	s_add_i32 s84, s79, s0
	s_lshl_b32 s86, s80, 3
	v_writelane_b32 v254, s0, 0
	s_mov_b64 s[4:5], s[88:89]
	s_cmp_gt_i32 s84, 0xe0ff
	v_mbcnt_lo_u32_b32 v98, -1, 0
	v_mbcnt_hi_u32_b32 v98, -1, v98
	s_cbranch_scc1 .LBB0_75
	s_lshl_b32 s0, s79, 14
	v_ashrrev_i32_e32 v14, 5, v98
	v_and_b32_e32 v2, 31, v98
	s_movk_i32 s1, 0x84
	s_add_i32 s0, s0, 0
	v_lshlrev_b32_e32 v4, 2, v2
	v_mul_lo_u32 v5, v14, s1
	v_add3_u32 v15, s0, v4, v5
	v_lshlrev_b32_e32 v5, 3, v98
	v_ashrrev_i32_e32 v4, 3, v98
	v_and_b32_e32 v12, 56, v5
	v_mul_u32_u24_e32 v5, 0x84, v12
	v_lshlrev_b32_e32 v6, 2, v4
	v_add3_u32 v16, s0, v5, v6
	s_load_dwordx2 s[0:1], s[4:5], 0x98
	v_add_u32_e32 v6, 8, v4
	v_add_u32_e32 v8, 16, v4
	v_add_u32_e32 v10, 24, v4
	s_mov_b32 s7, 0
	s_waitcnt lgkmcnt(0)
	s_add_u32 s3, s0, 0x200000
	v_mov_b32_e32 v3, 0
	v_ashrrev_i32_e32 v5, 31, v4
	v_ashrrev_i32_e32 v7, 31, v6
	v_ashrrev_i32_e32 v9, 31, v8
	v_ashrrev_i32_e32 v11, 31, v10
	s_addc_u32 s25, s1, 0
	s_lshl_b32 s26, s84, 5
	s_lshl_b32 s27, s80, 8
	s_lshl_b32 s28, s84, 3
	s_lshl_b32 s29, s80, 6
	s_movk_i32 s30, 0x1000
	s_movk_i32 s31, 0x2000
	s_movk_i32 s33, 0x3000
	s_movk_i32 s34, 0x4000
	s_movk_i32 s35, 0x5000
	s_movk_i32 s36, 0x6000
	s_movk_i32 s37, 0x7000
	s_mov_b32 s38, 0x8000
	s_mov_b32 s39, 0x9000
	s_mov_b32 s40, 0xa000
	s_mov_b32 s41, 0xb000
	s_mov_b32 s42, 0xc000
	s_mov_b32 s43, 0xd000
	s_mov_b32 s44, 0xe000
	s_mov_b32 s45, 0xf000
	s_mov_b64 s[10:11], 0x7000000
	s_mov_b32 s46, 0x10000
	s_mov_b32 s47, 0x14000
	s_mov_b32 s48, 0x18000
	s_mov_b32 s49, 0x1c000
	s_mov_b32 s50, 0x20000
	s_mov_b32 s51, 0x24000
	s_mov_b32 s52, 0x28000
	s_mov_b32 s53, 0x2c000
	s_mov_b32 s54, 0x30000
	s_mov_b32 s55, 0x34000
	s_mov_b32 s56, 0x38000
	s_mov_b32 s57, 0x3c000
	s_mov_b32 s58, 0x40000
	s_mov_b32 s59, 0x44000
	s_mov_b32 s60, 0x48000
	s_mov_b32 s61, 0x4c000
	s_mov_b32 s62, 0x50000
	s_mov_b32 s63, 0x54000
	s_mov_b32 s64, 0x58000
	s_mov_b32 s65, 0x5c000
	s_mov_b32 s66, 0x60000
	s_mov_b32 s67, 0x64000
	s_mov_b32 s68, 0x68000
	s_mov_b32 s69, 0x6c000
	s_mov_b32 s70, 0x70000
	s_mov_b32 s71, 0x74000
	s_mov_b32 s72, 0x78000
	s_mov_b32 s73, 0x7c000
	s_mov_b64 s[12:13], 0x6800000
	s_mov_b64 s[14:15], 0x5800000
	s_movk_i32 s74, 0x4800
	s_movk_i32 s75, 0x2400
	v_lshlrev_b32_e32 v2, 2, v2
	v_add_u32_e32 v17, 0x400, v15
	v_add_u32_e32 v18, 0x800, v15
	v_add_u32_e32 v19, 0xc00, v15
	v_add_u32_e32 v20, 0x1000, v15
	v_add_u32_e32 v21, 0x1400, v15
	v_add_u32_e32 v22, 0x1800, v15
	v_add_u32_e32 v23, 0x1c00, v15
	v_lshlrev_b32_e32 v12, 1, v12
	s_mov_b32 s76, s84
	s_branch .LBB0_22
